# down/out-proj residual epilogues: first load batch uses counted vmcnt per row group instead of vmcnt(0), so stores of early groups overlap the remaining loads
# speedup vs baseline: 1.0031x; 1.0031x over previous
; #define PG8_STAGE(bufoff, gbase, voff) do { _Pragma("unroll") for (int _i = 0; _i < 2; ++_i) \
;         __builtin_amdgcn_global_load_lds((const unsigned*)((const char*)(gbase) + (voff)[_i]), (LAS unsigned*)(lds + (bufoff) + ldsw + _i * 8192), 16, 0, 0); } while (0)
; #define PG8_LDA(dst, b, h) do { _Pragma("unroll") for (int m = 0; m < 4; ++m) _Pragma("unroll") for (int k = 0; k < 2; ++k) dst[m][k] = *(const LAS bf16x8*)(lds + PG8_SA(b, h) + aoff + m * 2048 + k * 1024); } while (0)
; #define PG8_LDB(dst, b, h) do { _Pragma("unroll") for (int n = 0; n < 2; ++n) _Pragma("unroll") for (int k = 0; k < 2; ++k) dst[n][k] = *(const LAS bf16x8*)(lds + PG8_SB(b, h) + boff + n * 2048 + k * 1024); } while (0)
; #define PG8_MMA(ai, bj, At, Bt) do { __builtin_amdgcn_s_setprio(1); _Pragma("unroll") for (int m = 0; m < 4; ++m) _Pragma("unroll") for (int n = 0; n < 2; ++n) _Pragma("unroll") for (int k = 0; k < 2; ++k) \
;         acc[ai][bj][m][n] = __builtin_amdgcn_mfma_f32_16x16x32_bf16(Bt[n][k], At[m][k], acc[ai][bj][m][n], 0, 0, 0); __builtin_amdgcn_s_setprio(0); } while (0)
; #define PG8_WAIT_V(n) asm volatile("s_waitcnt vmcnt(" #n ")" ::: "memory")
; #define PG8_WAIT_L(n) asm volatile("s_waitcnt lgkmcnt(" #n ")" ::: "memory")
; #define PG8_BAR __builtin_amdgcn_s_barrier()
; #define PG8_SCHED __builtin_amdgcn_sched_barrier(0)
; template <class Epi, bool ALIGN_EPI>
; __device__ __forceinline__ void gemm_phase(LAS unsigned char* lds, const Gemm g, int G, int cid, const Epi& E) {
;     ...
;             PG8_LDB(B0, 0, 0); PG8_LDB(B1, 0, 1); PG8_SCHED; PG8_LDA(At, 0, 0); PG8_STAGE(PG8_SA(1, 1), a1 + hA, voffA);
;             PG8_WAIT_V(8); PG8_WAIT_L(0); PG8_BAR; PG8_MMA(0, 0, At, B0); PG8_MMA(0, 1, At, B1); PG8_BAR; PG8_SCHED;
;             PG8_LDA(At, 0, 1); PG8_STAGE(PG8_SB(0, 0), b2, voffB); PG8_STAGE(PG8_SB(0, 1), b2 + hB, voffB); PG8_STAGE(PG8_SA(0, 0), a2, voffA);
;             PG8_WAIT_V(8); PG8_WAIT_L(0); PG8_BAR; PG8_MMA(1, 0, At, B0); PG8_MMA(1, 1, At, B1); PG8_BAR; PG8_SCHED;
.LBB0_727:
	s_add_u32 s42, s46, 0x100
	s_addc_u32 s43, s47, 0
	s_add_i32 s6, 0, 0x10000
	s_cmp_eq_u32 s77, 28
	s_cselect_b32 s51, s29, s43
	s_cselect_b32 s50, s28, s42
	s_cselect_b32 s49, s30, s76
	s_cselect_b32 s48, s74, s75
	s_add_i32 s7, 0, 0x14000
	v_add_u32_e32 v132, s6, v220
	v_add_u32_e32 v160, s7, v220
	ds_read_b128 v[112:115], v132
	ds_read_b128 v[116:119], v132 offset:1024
	ds_read_b128 v[128:131], v132 offset:2048
	ds_read_b128 v[132:135], v132 offset:3072
	ds_read_b128 v[140:143], v160
	ds_read_b128 v[144:147], v160 offset:1024
	ds_read_b128 v[156:159], v160 offset:2048
	ds_read_b128 v[160:163], v160 offset:3072
	v_lshl_add_u64 v[198:199], s[46:47], 0, v[184:185]
	s_add_i32 m0, s52, 0xc000
	ds_read_b128 v[164:167], v222
	ds_read_b128 v[168:171], v222 offset:1024
	ds_read_b128 v[172:175], v222 offset:2048
	ds_read_b128 v[176:179], v222 offset:3072
	ds_read_b128 v[188:191], v222 offset:4096
	ds_read_b128 v[206:209], v222 offset:5120
	ds_read_b128 v[210:213], v222 offset:6144
	ds_read_b128 v[214:217], v222 offset:7168
	global_load_lds_dwordx4 v[198:199], off
	v_lshl_add_u64 v[198:199], s[46:47], 0, v[186:187]
	s_add_i32 m0, s52, 0xe000
	s_nop 0
	global_load_lds_dwordx4 v[198:199], off
	s_add_i32 vcc_lo, s77, 2
	s_lshl_b32 vcc_lo, vcc_lo, 16
	s_lshl_b32 vcc_hi, s13, 21
	s_add_i32 vcc_lo, vcc_lo, vcc_hi
	s_lshl_b32 vcc_hi, s25, 4
	s_add_i32 vcc_lo, vcc_lo, vcc_hi
	s_lshl_b32 vcc_hi, s12, 10
	s_add_i32 vcc_lo, vcc_lo, vcc_hi
	s_add_u32 vcc_lo, s22, vcc_lo
	s_addc_u32 vcc_hi, s23, 0
	s_mov_b32 m0, 0x22c00
	s_nop 0
	global_load_lds_dwordx4 v224, vcc
	s_waitcnt vmcnt(9)
	s_waitcnt lgkmcnt(0)
	s_barrier
	s_setprio 1
	s_waitcnt lgkmcnt(0)
	v_mfma_f32_16x16x32_bf16 v[152:155], v[112:115], v[164:167], v[152:155]
	v_mfma_f32_16x16x32_bf16 v[148:151], v[128:131], v[164:167], v[148:151]
	v_mfma_f32_16x16x32_bf16 v[108:111], v[112:115], v[172:175], v[108:111]
	v_mfma_f32_16x16x32_bf16 v[104:107], v[128:131], v[172:175], v[104:107]
	v_mfma_f32_16x16x32_bf16 v[92:95], v[112:115], v[188:191], v[92:95]
	v_mfma_f32_16x16x32_bf16 v[88:91], v[128:131], v[188:191], v[88:91]
	v_mfma_f32_16x16x32_bf16 v[76:79], v[112:115], v[210:213], v[76:79]
	v_mfma_f32_16x16x32_bf16 v[72:75], v[128:131], v[210:213], v[72:75]
	v_mfma_f32_16x16x32_bf16 v[152:155], v[116:119], v[168:171], v[152:155]
	v_mfma_f32_16x16x32_bf16 v[148:151], v[132:135], v[168:171], v[148:151]
	v_mfma_f32_16x16x32_bf16 v[108:111], v[116:119], v[176:179], v[108:111]
	v_mfma_f32_16x16x32_bf16 v[104:107], v[132:135], v[176:179], v[104:107]
	v_mfma_f32_16x16x32_bf16 v[92:95], v[116:119], v[206:209], v[92:95]
	v_mfma_f32_16x16x32_bf16 v[88:91], v[132:135], v[206:209], v[88:91]
	v_mfma_f32_16x16x32_bf16 v[76:79], v[116:119], v[214:217], v[76:79]
	v_mfma_f32_16x16x32_bf16 v[72:75], v[132:135], v[214:217], v[72:75]
	s_setprio 0
	s_setprio 1
	v_mfma_f32_16x16x32_bf16 v[124:127], v[140:143], v[164:167], v[124:127]
	v_mfma_f32_16x16x32_bf16 v[120:123], v[156:159], v[164:167], v[120:123]
	v_mfma_f32_16x16x32_bf16 v[100:103], v[140:143], v[172:175], v[100:103]
	v_mfma_f32_16x16x32_bf16 v[96:99], v[156:159], v[172:175], v[96:99]
	v_mfma_f32_16x16x32_bf16 v[84:87], v[140:143], v[188:191], v[84:87]
	v_mfma_f32_16x16x32_bf16 v[80:83], v[156:159], v[188:191], v[80:83]
	v_mfma_f32_16x16x32_bf16 v[68:71], v[140:143], v[210:213], v[68:71]
	v_mfma_f32_16x16x32_bf16 v[64:67], v[156:159], v[210:213], v[64:67]
	v_mfma_f32_16x16x32_bf16 v[124:127], v[144:147], v[168:171], v[124:127]
	v_mfma_f32_16x16x32_bf16 v[120:123], v[160:163], v[168:171], v[120:123]
	v_mfma_f32_16x16x32_bf16 v[100:103], v[144:147], v[176:179], v[100:103]
	v_mfma_f32_16x16x32_bf16 v[96:99], v[160:163], v[176:179], v[96:99]
	v_mfma_f32_16x16x32_bf16 v[84:87], v[144:147], v[206:209], v[84:87]
	v_mfma_f32_16x16x32_bf16 v[80:83], v[160:163], v[206:209], v[80:83]
	v_mfma_f32_16x16x32_bf16 v[68:71], v[144:147], v[214:217], v[68:71]
	v_mfma_f32_16x16x32_bf16 v[64:67], v[160:163], v[214:217], v[64:67]
	s_setprio 0
	s_barrier
	s_add_i32 s6, s6, s25
	v_lshl_add_u64 v[198:199], s[48:49], 0, v[138:139]
	s_mov_b32 m0, s6
	ds_read_b128 v[164:167], v222 offset:16384
	ds_read_b128 v[168:171], v222 offset:17408
	ds_read_b128 v[172:175], v222 offset:18432
	ds_read_b128 v[176:179], v222 offset:19456
	ds_read_b128 v[188:191], v222 offset:20480
	ds_read_b128 v[206:209], v222 offset:21504
	ds_read_b128 v[210:213], v222 offset:22528
	ds_read_b128 v[214:217], v222 offset:23552
	global_load_lds_dwordx4 v[198:199], off
	s_add_i32 m0, s6, 0x2000
	s_add_u32 s46, s48, 0x2000
	v_lshl_add_u64 v[198:199], s[48:49], 0, v[136:137]
	s_addc_u32 s47, s49, 0
	s_add_i32 s6, s7, s25
	global_load_lds_dwordx4 v[198:199], off
	v_lshl_add_u64 v[198:199], s[46:47], 0, v[138:139]
	s_mov_b32 m0, s6
	v_lshl_add_u64 v[200:201], s[50:51], 0, v[180:181]
	global_load_lds_dwordx4 v[198:199], off
	v_lshl_add_u64 v[198:199], s[46:47], 0, v[136:137]
	s_add_i32 m0, s6, 0x2000
	s_nop 0
	global_load_lds_dwordx4 v[198:199], off
	v_lshl_add_u64 v[198:199], s[50:51], 0, v[182:183]
	s_mov_b32 m0, s52
	s_nop 0
	global_load_lds_dwordx4 v[198:199], off
	s_mov_b32 m0, s53
	s_nop 0
	global_load_lds_dwordx4 v[200:201], off
	s_waitcnt vmcnt(9)
	s_waitcnt lgkmcnt(0)
	s_barrier
; #define PG8_STAGE(bufoff, gbase, voff) do { _Pragma("unroll") for (int _i = 0; _i < 2; ++_i) \
;         __builtin_amdgcn_global_load_lds((const unsigned*)((const char*)(gbase) + (voff)[_i]), (LAS unsigned*)(lds + (bufoff) + ldsw + _i * 8192), 16, 0, 0); } while (0)
; #define PG8_LDA(dst, b, h) do { _Pragma("unroll") for (int m = 0; m < 4; ++m) _Pragma("unroll") for (int k = 0; k < 2; ++k) dst[m][k] = *(const LAS bf16x8*)(lds + PG8_SA(b, h) + aoff + m * 2048 + k * 1024); } while (0)
; #define PG8_LDB(dst, b, h) do { _Pragma("unroll") for (int n = 0; n < 2; ++n) _Pragma("unroll") for (int k = 0; k < 2; ++k) dst[n][k] = *(const LAS bf16x8*)(lds + PG8_SB(b, h) + boff + n * 2048 + k * 1024); } while (0)
; #define PG8_MMA(ai, bj, At, Bt) do { __builtin_amdgcn_s_setprio(1); _Pragma("unroll") for (int m = 0; m < 4; ++m) _Pragma("unroll") for (int n = 0; n < 2; ++n) _Pragma("unroll") for (int k = 0; k < 2; ++k) \
;         acc[ai][bj][m][n] = __builtin_amdgcn_mfma_f32_16x16x32_bf16(Bt[n][k], At[m][k], acc[ai][bj][m][n], 0, 0, 0); __builtin_amdgcn_s_setprio(0); } while (0)
; #define PG8_WAIT_V(n) asm volatile("s_waitcnt vmcnt(" #n ")" ::: "memory")
; #define PG8_WAIT_L(n) asm volatile("s_waitcnt lgkmcnt(" #n ")" ::: "memory")
; #define PG8_BAR __builtin_amdgcn_s_barrier()
; #define PG8_SCHED __builtin_amdgcn_sched_barrier(0)
; template <class Epi, bool ALIGN_EPI>
; __device__ __forceinline__ void gemm_phase(LAS unsigned char* lds, const Gemm g, int G, int cid, const Epi& E) {
;     ...
;             PG8_WAIT_V(8); PG8_WAIT_L(0); PG8_BAR; PG8_MMA(0, 0, At, B0); PG8_MMA(0, 1, At, B1); PG8_BAR; PG8_SCHED;
;             PG8_LDA(At, 0, 1); PG8_STAGE(PG8_SB(0, 0), b2, voffB); PG8_STAGE(PG8_SB(0, 1), b2 + hB, voffB); PG8_STAGE(PG8_SA(0, 0), a2, voffA);
;             PG8_WAIT_V(8); PG8_WAIT_L(0); PG8_BAR; PG8_MMA(1, 0, At, B0); PG8_MMA(1, 1, At, B1); PG8_BAR; PG8_SCHED;
;             PG8_LDB(B0, 1, 0); PG8_LDB(B1, 1, 1); PG8_SCHED; PG8_LDA(At, 1, 0); PG8_STAGE(PG8_SA(0, 1), a2 + hA, voffA);
;             PG8_WAIT_V(8); PG8_WAIT_L(0); PG8_BAR; PG8_MMA(0, 0, At, B0); PG8_MMA(0, 1, At, B1); PG8_BAR; PG8_SCHED;
	s_setprio 1
	s_waitcnt lgkmcnt(0)
	v_mfma_f32_16x16x32_bf16 v[60:63], v[112:115], v[164:167], v[60:63]
	v_mfma_f32_16x16x32_bf16 v[56:59], v[128:131], v[164:167], v[56:59]
	v_mfma_f32_16x16x32_bf16 v[44:47], v[112:115], v[172:175], v[44:47]
	v_mfma_f32_16x16x32_bf16 v[40:43], v[128:131], v[172:175], v[40:43]
	v_mfma_f32_16x16x32_bf16 v[28:31], v[112:115], v[188:191], v[28:31]
	v_mfma_f32_16x16x32_bf16 v[24:27], v[128:131], v[188:191], v[24:27]
	v_mfma_f32_16x16x32_bf16 v[12:15], v[112:115], v[210:213], v[12:15]
	v_mfma_f32_16x16x32_bf16 v[8:11], v[128:131], v[210:213], v[8:11]
	v_mfma_f32_16x16x32_bf16 v[60:63], v[116:119], v[168:171], v[60:63]
	v_mfma_f32_16x16x32_bf16 v[56:59], v[132:135], v[168:171], v[56:59]
	v_mfma_f32_16x16x32_bf16 v[44:47], v[116:119], v[176:179], v[44:47]
	v_mfma_f32_16x16x32_bf16 v[40:43], v[132:135], v[176:179], v[40:43]
	v_mfma_f32_16x16x32_bf16 v[28:31], v[116:119], v[206:209], v[28:31]
	v_mfma_f32_16x16x32_bf16 v[24:27], v[132:135], v[206:209], v[24:27]
	v_mfma_f32_16x16x32_bf16 v[12:15], v[116:119], v[214:217], v[12:15]
	v_mfma_f32_16x16x32_bf16 v[8:11], v[132:135], v[214:217], v[8:11]
	s_setprio 0
	s_setprio 1
	v_mfma_f32_16x16x32_bf16 v[52:55], v[140:143], v[164:167], v[52:55]
	v_mfma_f32_16x16x32_bf16 v[48:51], v[156:159], v[164:167], v[48:51]
	v_mfma_f32_16x16x32_bf16 v[36:39], v[140:143], v[172:175], v[36:39]
	v_mfma_f32_16x16x32_bf16 v[32:35], v[156:159], v[172:175], v[32:35]
	v_mfma_f32_16x16x32_bf16 v[20:23], v[140:143], v[188:191], v[20:23]
	v_mfma_f32_16x16x32_bf16 v[16:19], v[156:159], v[188:191], v[16:19]
	v_mfma_f32_16x16x32_bf16 v[4:7], v[140:143], v[210:213], v[4:7]
	v_mfma_f32_16x16x32_bf16 v[0:3], v[156:159], v[210:213], v[0:3]
	v_mfma_f32_16x16x32_bf16 v[52:55], v[144:147], v[168:171], v[52:55]
	v_mfma_f32_16x16x32_bf16 v[48:51], v[160:163], v[168:171], v[48:51]
	v_mfma_f32_16x16x32_bf16 v[36:39], v[144:147], v[176:179], v[36:39]
	v_mfma_f32_16x16x32_bf16 v[32:35], v[160:163], v[176:179], v[32:35]
	v_mfma_f32_16x16x32_bf16 v[20:23], v[144:147], v[206:209], v[20:23]
	v_mfma_f32_16x16x32_bf16 v[16:19], v[160:163], v[206:209], v[16:19]
	v_mfma_f32_16x16x32_bf16 v[4:7], v[144:147], v[214:217], v[4:7]
	v_mfma_f32_16x16x32_bf16 v[0:3], v[160:163], v[214:217], v[0:3]
	s_setprio 0
	s_barrier
	s_add_i32 s6, 0, 0x18000
	s_add_i32 s7, 0, 0x1c000
	v_add_u32_e32 v132, s6, v220
	v_add_u32_e32 v160, s7, v220
	ds_read_b128 v[112:115], v132
	ds_read_b128 v[116:119], v132 offset:1024
	ds_read_b128 v[128:131], v132 offset:2048
	ds_read_b128 v[132:135], v132 offset:3072
	ds_read_b128 v[140:143], v160
	ds_read_b128 v[144:147], v160 offset:1024
	ds_read_b128 v[156:159], v160 offset:2048
	ds_read_b128 v[160:163], v160 offset:3072
	s_add_u32 s46, s50, 0x84000
	s_addc_u32 s47, s51, 0
	s_mov_b32 m0, s54
	v_lshl_add_u64 v[218:219], s[46:47], 0, v[182:183]
	ds_read_b128 v[164:167], v222 offset:32768
	ds_read_b128 v[168:171], v222 offset:33792
	ds_read_b128 v[172:175], v222 offset:34816
	ds_read_b128 v[176:179], v222 offset:35840
	ds_read_b128 v[188:191], v222 offset:36864
	ds_read_b128 v[206:209], v222 offset:37888
	ds_read_b128 v[210:213], v222 offset:38912
	ds_read_b128 v[214:217], v222 offset:39936
	global_load_lds_dwordx4 v[218:219], off
	v_lshl_add_u64 v[218:219], s[46:47], 0, v[180:181]
	s_mov_b32 m0, s55
	s_nop 0
	global_load_lds_dwordx4 v[218:219], off
	s_add_u32 vcc_lo, vcc_lo, 0x2000
	s_addc_u32 vcc_hi, vcc_hi, 0
	s_mov_b32 m0, 0x22c00
	s_nop 0
	global_load_lds_dwordx4 v224, vcc
	s_waitcnt vmcnt(9)
	s_waitcnt lgkmcnt(0)
	s_barrier
	s_setprio 1
	s_waitcnt lgkmcnt(0)
	v_mfma_f32_16x16x32_bf16 v[152:155], v[112:115], v[164:167], v[152:155]
	v_mfma_f32_16x16x32_bf16 v[148:151], v[128:131], v[164:167], v[148:151]
	v_mfma_f32_16x16x32_bf16 v[108:111], v[112:115], v[172:175], v[108:111]
	v_mfma_f32_16x16x32_bf16 v[104:107], v[128:131], v[172:175], v[104:107]
	v_mfma_f32_16x16x32_bf16 v[92:95], v[112:115], v[188:191], v[92:95]
	v_mfma_f32_16x16x32_bf16 v[88:91], v[128:131], v[188:191], v[88:91]
	v_mfma_f32_16x16x32_bf16 v[76:79], v[112:115], v[210:213], v[76:79]
	v_mfma_f32_16x16x32_bf16 v[72:75], v[128:131], v[210:213], v[72:75]
	v_mfma_f32_16x16x32_bf16 v[152:155], v[116:119], v[168:171], v[152:155]
	v_mfma_f32_16x16x32_bf16 v[148:151], v[132:135], v[168:171], v[148:151]
	v_mfma_f32_16x16x32_bf16 v[108:111], v[116:119], v[176:179], v[108:111]
	v_mfma_f32_16x16x32_bf16 v[104:107], v[132:135], v[176:179], v[104:107]
	v_mfma_f32_16x16x32_bf16 v[92:95], v[116:119], v[206:209], v[92:95]
	v_mfma_f32_16x16x32_bf16 v[88:91], v[132:135], v[206:209], v[88:91]
	v_mfma_f32_16x16x32_bf16 v[76:79], v[116:119], v[214:217], v[76:79]
	v_mfma_f32_16x16x32_bf16 v[72:75], v[132:135], v[214:217], v[72:75]
	s_setprio 0
	s_setprio 1
	v_mfma_f32_16x16x32_bf16 v[124:127], v[140:143], v[164:167], v[124:127]
	v_mfma_f32_16x16x32_bf16 v[120:123], v[156:159], v[164:167], v[120:123]
	v_mfma_f32_16x16x32_bf16 v[100:103], v[140:143], v[172:175], v[100:103]
	v_mfma_f32_16x16x32_bf16 v[96:99], v[156:159], v[172:175], v[96:99]
	v_mfma_f32_16x16x32_bf16 v[84:87], v[140:143], v[188:191], v[84:87]
	v_mfma_f32_16x16x32_bf16 v[80:83], v[156:159], v[188:191], v[80:83]
	v_mfma_f32_16x16x32_bf16 v[68:71], v[140:143], v[210:213], v[68:71]
	v_mfma_f32_16x16x32_bf16 v[64:67], v[156:159], v[210:213], v[64:67]
	v_mfma_f32_16x16x32_bf16 v[124:127], v[144:147], v[168:171], v[124:127]
	v_mfma_f32_16x16x32_bf16 v[120:123], v[160:163], v[168:171], v[120:123]
	v_mfma_f32_16x16x32_bf16 v[100:103], v[144:147], v[176:179], v[100:103]
	v_mfma_f32_16x16x32_bf16 v[96:99], v[160:163], v[176:179], v[96:99]
	v_mfma_f32_16x16x32_bf16 v[84:87], v[144:147], v[206:209], v[84:87]
	v_mfma_f32_16x16x32_bf16 v[80:83], v[160:163], v[206:209], v[80:83]
	v_mfma_f32_16x16x32_bf16 v[68:71], v[144:147], v[214:217], v[68:71]
	v_mfma_f32_16x16x32_bf16 v[64:67], v[160:163], v[214:217], v[64:67]
	s_setprio 0
	s_barrier
; #define PG8_MMA(ai, bj, At, Bt) do { __builtin_amdgcn_s_setprio(1); _Pragma("unroll") for (int m = 0; m < 4; ++m) _Pragma("unroll") for (int n = 0; n < 2; ++n) _Pragma("unroll") for (int k = 0; k < 2; ++k) \
;         acc[ai][bj][m][n] = __builtin_amdgcn_mfma_f32_16x16x32_bf16(Bt[n][k], At[m][k], acc[ai][bj][m][n], 0, 0, 0); __builtin_amdgcn_s_setprio(0); } while (0)
; #define PG8_WAIT_V(n) asm volatile("s_waitcnt vmcnt(" #n ")" ::: "memory")
; #define PG8_WAIT_L(n) asm volatile("s_waitcnt lgkmcnt(" #n ")" ::: "memory")
; #define PG8_BAR __builtin_amdgcn_s_barrier()
; #define PG8_SCHED __builtin_amdgcn_sched_barrier(0)
; template <class Epi, bool ALIGN_EPI>
; __device__ __forceinline__ void gemm_phase(LAS unsigned char* lds, const Gemm g, int G, int cid, const Epi& E) {
;     ...
;             PG8_WAIT_V(8); PG8_WAIT_L(0); PG8_BAR; PG8_MMA(1, 0, At, B0); PG8_MMA(1, 1, At, B1); PG8_BAR; PG8_SCHED;
;         }
;     __device__ __forceinline__ void operator()(const f32x4 (&acc)[2][2][4][2], const Unit& u, int wr, int wc, int fr, int fq, const LAS float*) const {
;     ...
;         for (int am = 0; am < NB; ++am) { const int ai = am / (NB / 2), m0 = (am % (NB / 2)) * MB;
;             f32x4 xo[4][2][2];
; #pragma unroll
;             for (int m = m0; m < m0 + MB; ++m) { const float* xr = Xs + (size_t)(row0 + ai * HALF + m * 16) * DM + col0;
; #pragma unroll
;                 for (int bj = 0; bj < 2; ++bj) { xo[m][bj][0] = *(const f32x4*)(xr + bj * HALF); xo[m][bj][1] = *(const f32x4*)(xr + bj * HALF + 4); } }
	s_add_u32 s46, s48, 0x40000
	s_addc_u32 s47, s49, 0
	s_add_i32 s6, s6, s25
	v_lshl_add_u64 v[218:219], s[46:47], 0, v[138:139]
	s_mov_b32 m0, s6
	ds_read_b128 v[164:167], v222 offset:49152
	ds_read_b128 v[168:171], v222 offset:50176
	ds_read_b128 v[172:175], v222 offset:51200
	ds_read_b128 v[176:179], v222 offset:52224
	ds_read_b128 v[188:191], v222 offset:53248
	ds_read_b128 v[206:209], v222 offset:54272
	ds_read_b128 v[210:213], v222 offset:55296
	ds_read_b128 v[214:217], v222 offset:56320
	global_load_lds_dwordx4 v[218:219], off
	s_add_i32 m0, s6, 0x2000
	v_lshl_add_u64 v[218:219], s[46:47], 0, v[136:137]
	s_add_u32 s46, s48, 0x42000
	s_addc_u32 s47, s49, 0
	s_add_i32 s6, s7, s25
	global_load_lds_dwordx4 v[218:219], off
	v_lshl_add_u64 v[218:219], s[46:47], 0, v[138:139]
	s_mov_b32 m0, s6
	v_lshl_add_u64 v[198:199], v[198:199], 0, s[36:37]
	global_load_lds_dwordx4 v[218:219], off
	v_lshl_add_u64 v[218:219], s[46:47], 0, v[136:137]
	s_add_i32 m0, s6, 0x2000
	s_nop 0
	global_load_lds_dwordx4 v[218:219], off
	s_mov_b32 m0, s58
	s_nop 0
	global_load_lds_dwordx4 v[198:199], off
	v_lshl_add_u64 v[198:199], v[200:201], 0, s[36:37]
	s_mov_b32 m0, s59
	s_nop 0
	global_load_lds_dwordx4 v[198:199], off
	s_waitcnt vmcnt(9)
	s_waitcnt lgkmcnt(0)
	s_barrier
	s_setprio 1
	s_waitcnt lgkmcnt(0)
	v_mfma_f32_16x16x32_bf16 v[60:63], v[112:115], v[164:167], v[60:63]
	v_mfma_f32_16x16x32_bf16 v[56:59], v[128:131], v[164:167], v[56:59]
	v_mfma_f32_16x16x32_bf16 v[44:47], v[112:115], v[172:175], v[44:47]
	v_mfma_f32_16x16x32_bf16 v[40:43], v[128:131], v[172:175], v[40:43]
	v_mfma_f32_16x16x32_bf16 v[28:31], v[112:115], v[188:191], v[28:31]
	v_mfma_f32_16x16x32_bf16 v[24:27], v[128:131], v[188:191], v[24:27]
	v_mfma_f32_16x16x32_bf16 v[12:15], v[112:115], v[210:213], v[12:15]
	v_mfma_f32_16x16x32_bf16 v[8:11], v[128:131], v[210:213], v[8:11]
	v_mfma_f32_16x16x32_bf16 v[60:63], v[116:119], v[168:171], v[60:63]
	v_mfma_f32_16x16x32_bf16 v[56:59], v[132:135], v[168:171], v[56:59]
	v_mfma_f32_16x16x32_bf16 v[44:47], v[116:119], v[176:179], v[44:47]
	v_mfma_f32_16x16x32_bf16 v[40:43], v[132:135], v[176:179], v[40:43]
	v_mfma_f32_16x16x32_bf16 v[28:31], v[116:119], v[206:209], v[28:31]
	v_mfma_f32_16x16x32_bf16 v[24:27], v[132:135], v[206:209], v[24:27]
	v_mfma_f32_16x16x32_bf16 v[12:15], v[116:119], v[214:217], v[12:15]
	v_mfma_f32_16x16x32_bf16 v[8:11], v[132:135], v[214:217], v[8:11]
	s_setprio 0
	s_setprio 1
	v_mfma_f32_16x16x32_bf16 v[52:55], v[140:143], v[164:167], v[52:55]
	v_mfma_f32_16x16x32_bf16 v[48:51], v[156:159], v[164:167], v[48:51]
	v_mfma_f32_16x16x32_bf16 v[36:39], v[140:143], v[172:175], v[36:39]
	v_mfma_f32_16x16x32_bf16 v[32:35], v[156:159], v[172:175], v[32:35]
	v_mfma_f32_16x16x32_bf16 v[20:23], v[140:143], v[188:191], v[20:23]
	v_mfma_f32_16x16x32_bf16 v[16:19], v[156:159], v[188:191], v[16:19]
	v_mfma_f32_16x16x32_bf16 v[4:7], v[140:143], v[210:213], v[4:7]
	v_mfma_f32_16x16x32_bf16 v[0:3], v[156:159], v[210:213], v[0:3]
	v_mfma_f32_16x16x32_bf16 v[52:55], v[144:147], v[168:171], v[52:55]
	v_mfma_f32_16x16x32_bf16 v[48:51], v[160:163], v[168:171], v[48:51]
	v_mfma_f32_16x16x32_bf16 v[36:39], v[144:147], v[176:179], v[36:39]
	v_mfma_f32_16x16x32_bf16 v[32:35], v[160:163], v[176:179], v[32:35]
	v_mfma_f32_16x16x32_bf16 v[20:23], v[144:147], v[206:209], v[20:23]
	v_mfma_f32_16x16x32_bf16 v[16:19], v[160:163], v[206:209], v[16:19]
	v_mfma_f32_16x16x32_bf16 v[4:7], v[144:147], v[214:217], v[4:7]
	v_mfma_f32_16x16x32_bf16 v[0:3], v[160:163], v[214:217], v[0:3]
	s_setprio 0
	s_barrier
	s_add_i32 s77, s77, 2
	s_add_u32 s75, s75, 0x80000
	s_addc_u32 s76, s76, 0
	s_cmp_gt_u32 s77, 29
	s_mov_b64 s[46:47], s[42:43]
	s_cbranch_scc0 .LBB0_727
	v_lshl_or_b32 v188, s12, 8, v221
	v_lshl_add_u32 v190, s13, 8, v197
	v_ashrrev_i32_e32 v189, 31, v188
	v_lshlrev_b64 v[198:199], 2, v[188:189]
	v_ashrrev_i32_e32 v191, 31, v190
	v_lshl_add_u64 v[206:207], s[22:23], 0, v[198:199]
	v_lshlrev_b64 v[200:201], 13, v[190:191]
	v_lshl_add_u64 v[112:113], v[206:207], 0, v[200:201]
	global_load_dwordx4 v[224:227], v[112:113], off offset:16
	global_load_dwordx4 v[228:231], v[112:113], off
	global_load_dwordx4 v[232:235], v[112:113], off offset:528
	global_load_dwordx4 v[244:247], v[112:113], off offset:512
	v_or_b32_e32 v214, 16, v190
	v_ashrrev_i32_e32 v215, 31, v214
	v_or_b32_e32 v210, 32, v190
	v_or_b32_e32 v208, 48, v190
	v_lshlrev_b64 v[218:219], 13, v[214:215]
	v_ashrrev_i32_e32 v211, 31, v210
	v_ashrrev_i32_e32 v209, 31, v208
	v_lshl_add_u64 v[112:113], v[206:207], 0, v[218:219]
	v_lshlrev_b64 v[216:217], 13, v[210:211]
	v_lshlrev_b64 v[212:213], 13, v[208:209]
	global_load_dwordx4 v[172:175], v[112:113], off offset:16
	global_load_dwordx4 v[176:179], v[112:113], off
	global_load_dwordx4 v[164:167], v[112:113], off offset:528
	global_load_dwordx4 v[168:171], v[112:113], off offset:512
	v_lshl_add_u64 v[112:113], v[206:207], 0, v[216:217]
	v_lshl_add_u64 v[116:117], v[206:207], 0, v[212:213]
	global_load_dwordx4 v[156:159], v[112:113], off offset:16
	global_load_dwordx4 v[160:163], v[112:113], off
	global_load_dwordx4 v[128:131], v[112:113], off offset:528
	global_load_dwordx4 v[144:147], v[112:113], off offset:512
	global_load_dwordx4 v[132:135], v[116:117], off offset:16
	global_load_dwordx4 v[140:143], v[116:117], off
	s_nop 0
	global_load_dwordx4 v[112:115], v[116:117], off offset:528
	s_nop 0
	global_load_dwordx4 v[116:119], v[116:117], off offset:512
	v_lshl_add_u64 v[200:201], s[82:83], 0, v[200:201]
	v_lshl_add_u64 v[198:199], v[200:201], 0, v[198:199]
	v_mov_b64_e32 v[200:201], s[4:5]
	s_lshl_b32 s42, s12, 2
	v_mad_i64_i32 v[200:201], s[12:13], v190, s66, v[200:201]
	v_lshl_add_u64 v[200:201], v[188:189], 1, v[200:201]
	s_ashr_i32 s43, s42, 31
	s_waitcnt vmcnt(12)
; __device__ __forceinline__ unsigned cvt_pk_bf16(float lo, float hi) { unsigned r; asm volatile("v_cvt_pk_bf16_f32 %0, %1, %2" : "=v"(r) : "v"(lo), "v"(hi)); return r; }
;     __device__ __forceinline__ void operator()(const f32x4 (&acc)[2][2][4][2], const Unit& u, int wr, int wc, int fr, int fq, const LAS float*) const {
;     ...
;             for (int m = m0; m < m0 + MB; ++m) { const int row = row0 + ai * HALF + m * 16; float ss = 0.f;
;                 float* xr = X + (size_t)row * DM + col0; bf16_t* xb = XB + (size_t)row * ALD + col0;
; #pragma unroll
;                 for (int bj = 0; bj < 2; ++bj) { f32x4 x0 = xo[m][bj][0], x1 = xo[m][bj][1];
;                     if (HB) { x0 += (acc[ai][bj][m][0] + bv[bj][0]) * sv[bj][0]; x1 += (acc[ai][bj][m][1] + bv[bj][1]) * sv[bj][1]; } else { x0 += acc[ai][bj][m][0]; x1 += acc[ai][bj][m][1]; }
;                     *(f32x4*)(xr + bj * HALF) = x0; *(f32x4*)(xr + bj * HALF + 4) = x1;
;                     ss += (x0[0] * x0[0] + x0[1] * x0[1]) + (x0[2] * x0[2] + x0[3] * x0[3]) + (x1[0] * x1[0] + x1[1] * x1[1]) + (x1[2] * x1[2] + x1[3] * x1[3]);
;                     u32x4 w; w.x = cvt_pk_bf16(x0[0], x0[1]); w.y = cvt_pk_bf16(x0[2], x0[3]); w.z = cvt_pk_bf16(x1[0], x1[1]); w.w = cvt_pk_bf16(x1[2], x1[3]);
;                     if (feeds) *(u32x4*)(xb + bj * HALF) = w; }
;                 ss += __shfl_xor(ss, 16); ss += __shfl_xor(ss, 32);
;                 if (fq == 0 && feeds) part[(size_t)row * NPART + u.pn * 4 + wc] = ss; }
	v_pk_add_f32 v[148:149], v[148:149], v[224:225]
	v_pk_add_f32 v[154:155], v[154:155], v[230:231]
	v_pk_add_f32 v[152:153], v[152:153], v[228:229]
	v_mul_f32_e32 v224, v155, v155
	v_mul_f32_e32 v223, v153, v153
	v_fmac_f32_e32 v223, v152, v152
	v_fmac_f32_e32 v224, v154, v154
	v_add_f32_e32 v223, v223, v224
	v_mul_f32_e32 v224, v149, v149
	v_pk_add_f32 v[126:127], v[126:127], v[246:247]
	v_pk_add_f32 v[124:125], v[124:125], v[244:245]
	v_pk_add_f32 v[150:151], v[150:151], v[226:227]
	global_store_dwordx4 v[198:199], v[152:155], off
	global_store_dwordx4 v[198:199], v[148:151], off offset:16
	v_fmac_f32_e32 v224, v148, v148
	v_cvt_pk_bf16_f32 v152, v152, v153
	v_cvt_pk_bf16_f32 v153, v154, v155
	v_cvt_pk_bf16_f32 v154, v148, v149
	v_pk_add_f32 v[120:121], v[120:121], v[232:233]
	v_mul_f32_e32 v148, v125, v125
	v_mul_f32_e32 v149, v127, v127
	v_fmac_f32_e32 v148, v124, v124
	v_fmac_f32_e32 v149, v126, v126
	v_add_f32_e32 v148, v148, v149
	v_mul_f32_e32 v149, v121, v121
	v_cvt_pk_bf16_f32 v155, v150, v151
	global_store_dwordx4 v[200:201], v[152:155], off
	v_pk_add_f32 v[122:123], v[122:123], v[234:235]
	global_store_dwordx4 v[198:199], v[124:127], off offset:512
	global_store_dwordx4 v[198:199], v[120:123], off offset:528
	v_fmac_f32_e32 v149, v120, v120
	v_cvt_pk_bf16_f32 v124, v124, v125
	v_cvt_pk_bf16_f32 v125, v126, v127
	v_cvt_pk_bf16_f32 v126, v120, v121
	v_add_f32_e32 v223, v223, v224
	v_and_b32_e32 v121, 64, v239
	v_mul_f32_e32 v224, v151, v151
	v_add_f32_e32 v148, v148, v149
	v_mul_f32_e32 v149, v123, v123
	v_xor_b32_e32 v120, 16, v239
	v_add_u32_e32 v121, 64, v121
	v_fmac_f32_e32 v224, v150, v150
	v_fmac_f32_e32 v149, v122, v122
	v_cmp_lt_i32_e32 vcc, v120, v121
	v_add_f32_e32 v223, v224, v223
	v_add_f32_e32 v148, v149, v148
	v_cndmask_b32_e32 v120, v239, v120, vcc
	v_add_f32_e32 v148, v223, v148
	v_cvt_pk_bf16_f32 v127, v122, v123
	global_store_dwordx4 v[200:201], v[124:127], off offset:256
	v_xor_b32_e32 v122, 32, v239
	v_cmp_lt_i32_e32 vcc, v122, v121
	v_lshlrev_b32_e32 v126, 2, v120
	ds_bpermute_b32 v120, v126, v148
	v_cndmask_b32_e32 v121, v239, v122, vcc
	v_lshlrev_b32_e32 v127, 2, v121
	s_waitcnt lgkmcnt(0)
	v_add_f32_e32 v120, v148, v120
	ds_bpermute_b32 v121, v127, v120
	s_and_saveexec_b64 s[46:47], s[38:39]
	s_cbranch_execz .LBB0_730
	v_lshlrev_b64 v[122:123], 7, v[190:191]
	v_lshl_add_u64 v[122:123], s[94:95], 0, v[122:123]
	v_lshl_add_u64 v[122:123], s[42:43], 2, v[122:123]
	s_lshl_b32 s30, s57, 2
	v_lshl_add_u64 v[122:123], v[122:123], 0, s[30:31]
	s_waitcnt lgkmcnt(0)
	v_add_f32_e32 v120, v120, v121
	global_store_dword v[122:123], v120, off
.LBB0_730:
	s_or_b64 exec, exec, s[46:47]
	s_waitcnt vmcnt(14)
	v_pk_add_f32 v[110:111], v[110:111], v[178:179]
	v_pk_add_f32 v[108:109], v[108:109], v[176:177]
	v_mul_f32_e32 v125, v111, v111
	v_mul_f32_e32 v124, v109, v109
	s_waitcnt lgkmcnt(0)
	v_lshl_add_u64 v[120:121], s[82:83], 0, v[218:219]
	v_pk_add_f32 v[104:105], v[104:105], v[172:173]
	v_fmac_f32_e32 v124, v108, v108
	v_fmac_f32_e32 v125, v110, v110
	v_lshl_add_u64 v[120:121], v[188:189], 2, v[120:121]
	v_add_f32_e32 v124, v124, v125
	v_mul_f32_e32 v125, v105, v105
	v_pk_add_f32 v[102:103], v[102:103], v[170:171]
	v_pk_add_f32 v[100:101], v[100:101], v[168:169]
	v_pk_add_f32 v[106:107], v[106:107], v[174:175]
	global_store_dwordx4 v[120:121], v[108:111], off
	global_store_dwordx4 v[120:121], v[104:107], off offset:16
	v_fmac_f32_e32 v125, v104, v104
	v_cvt_pk_bf16_f32 v108, v108, v109
	v_cvt_pk_bf16_f32 v109, v110, v111
	v_cvt_pk_bf16_f32 v110, v104, v105
	v_add_f32_e32 v124, v124, v125
	v_pk_add_f32 v[104:105], v[96:97], v[164:165]
	v_mul_f32_e32 v96, v101, v101
	v_mul_f32_e32 v97, v103, v103
	v_fmac_f32_e32 v96, v100, v100
	v_fmac_f32_e32 v97, v102, v102
	v_mul_f32_e32 v125, v107, v107
	v_add_f32_e32 v96, v96, v97
	v_mul_f32_e32 v97, v105, v105
	v_fmac_f32_e32 v125, v106, v106
	v_cvt_pk_bf16_f32 v111, v106, v107
	v_pk_add_f32 v[106:107], v[98:99], v[166:167]
	v_fmac_f32_e32 v97, v104, v104
	v_add_f32_e32 v96, v96, v97
	v_mul_f32_e32 v97, v107, v107
	v_fmac_f32_e32 v97, v106, v106
	v_add_f32_e32 v124, v125, v124
	v_add_f32_e32 v96, v97, v96
	v_add_f32_e32 v96, v124, v96
	ds_bpermute_b32 v97, v126, v96
	v_mov_b64_e32 v[122:123], s[4:5]
	v_mad_i64_i32 v[122:123], s[12:13], v214, s66, v[122:123]
	v_lshl_add_u64 v[122:123], v[188:189], 1, v[122:123]
	s_waitcnt lgkmcnt(0)
	v_add_f32_e32 v96, v96, v97
	ds_bpermute_b32 v97, v127, v96
	global_store_dwordx4 v[122:123], v[108:111], off
	global_store_dwordx4 v[120:121], v[100:103], off offset:512
	global_store_dwordx4 v[120:121], v[104:107], off offset:528
	v_cvt_pk_bf16_f32 v98, v100, v101
	v_cvt_pk_bf16_f32 v99, v102, v103
	s_nop 0
	v_cvt_pk_bf16_f32 v100, v104, v105
	v_cvt_pk_bf16_f32 v101, v106, v107
	global_store_dwordx4 v[122:123], v[98:101], off offset:256
	s_and_saveexec_b64 s[46:47], s[38:39]
	s_cbranch_execz .LBB0_732
	v_lshlrev_b64 v[98:99], 7, v[214:215]
	v_lshl_add_u64 v[98:99], s[94:95], 0, v[98:99]
	v_lshl_add_u64 v[98:99], s[42:43], 2, v[98:99]
	s_lshl_b32 s30, s57, 2
	v_lshl_add_u64 v[98:99], v[98:99], 0, s[30:31]
	s_waitcnt lgkmcnt(0)
	v_add_f32_e32 v96, v96, v97
	global_store_dword v[98:99], v96, off
; __device__ __forceinline__ unsigned cvt_pk_bf16(float lo, float hi) { unsigned r; asm volatile("v_cvt_pk_bf16_f32 %0, %1, %2" : "=v"(r) : "v"(lo), "v"(hi)); return r; }
;     __device__ __forceinline__ void operator()(const f32x4 (&acc)[2][2][4][2], const Unit& u, int wr, int wc, int fr, int fq, const LAS float*) const {
;     ...
;             for (int m = m0; m < m0 + MB; ++m) { const int row = row0 + ai * HALF + m * 16; float ss = 0.f;
;                 float* xr = X + (size_t)row * DM + col0; bf16_t* xb = XB + (size_t)row * ALD + col0;
; #pragma unroll
;                 for (int bj = 0; bj < 2; ++bj) { f32x4 x0 = xo[m][bj][0], x1 = xo[m][bj][1];
;                     if (HB) { x0 += (acc[ai][bj][m][0] + bv[bj][0]) * sv[bj][0]; x1 += (acc[ai][bj][m][1] + bv[bj][1]) * sv[bj][1]; } else { x0 += acc[ai][bj][m][0]; x1 += acc[ai][bj][m][1]; }
;                     *(f32x4*)(xr + bj * HALF) = x0; *(f32x4*)(xr + bj * HALF + 4) = x1;
;                     ss += (x0[0] * x0[0] + x0[1] * x0[1]) + (x0[2] * x0[2] + x0[3] * x0[3]) + (x1[0] * x1[0] + x1[1] * x1[1]) + (x1[2] * x1[2] + x1[3] * x1[3]);
;                     u32x4 w; w.x = cvt_pk_bf16(x0[0], x0[1]); w.y = cvt_pk_bf16(x0[2], x0[3]); w.z = cvt_pk_bf16(x1[0], x1[1]); w.w = cvt_pk_bf16(x1[2], x1[3]);
;                     if (feeds) *(u32x4*)(xb + bj * HALF) = w; }
;                 ss += __shfl_xor(ss, 16); ss += __shfl_xor(ss, 32);
;                 if (fq == 0 && feeds) part[(size_t)row * NPART + u.pn * 4 + wc] = ss; }
.LBB0_732:
	s_or_b64 exec, exec, s[46:47]
	s_waitcnt vmcnt(16)
	v_pk_add_f32 v[94:95], v[94:95], v[162:163]
	v_pk_add_f32 v[92:93], v[92:93], v[160:161]
	v_mul_f32_e32 v101, v95, v95
	v_mul_f32_e32 v100, v93, v93
	s_waitcnt lgkmcnt(0)
	v_lshl_add_u64 v[96:97], s[82:83], 0, v[216:217]
	v_pk_add_f32 v[88:89], v[88:89], v[156:157]
	v_fmac_f32_e32 v100, v92, v92
	v_fmac_f32_e32 v101, v94, v94
	v_lshl_add_u64 v[96:97], v[188:189], 2, v[96:97]
	v_add_f32_e32 v100, v100, v101
	v_mul_f32_e32 v101, v89, v89
	v_pk_add_f32 v[86:87], v[86:87], v[146:147]
	v_pk_add_f32 v[84:85], v[84:85], v[144:145]
	v_pk_add_f32 v[90:91], v[90:91], v[158:159]
	global_store_dwordx4 v[96:97], v[92:95], off
	global_store_dwordx4 v[96:97], v[88:91], off offset:16
	v_fmac_f32_e32 v101, v88, v88
	v_cvt_pk_bf16_f32 v92, v92, v93
	v_cvt_pk_bf16_f32 v93, v94, v95
	v_cvt_pk_bf16_f32 v94, v88, v89
	v_add_f32_e32 v100, v100, v101
	v_pk_add_f32 v[88:89], v[80:81], v[128:129]
	v_mul_f32_e32 v80, v85, v85
	v_mul_f32_e32 v81, v87, v87
	v_fmac_f32_e32 v80, v84, v84
	v_fmac_f32_e32 v81, v86, v86
	v_mul_f32_e32 v101, v91, v91
	v_add_f32_e32 v80, v80, v81
	v_mul_f32_e32 v81, v89, v89
	v_fmac_f32_e32 v101, v90, v90
	v_cvt_pk_bf16_f32 v95, v90, v91
	v_pk_add_f32 v[90:91], v[82:83], v[130:131]
	v_fmac_f32_e32 v81, v88, v88
	v_add_f32_e32 v80, v80, v81
	v_mul_f32_e32 v81, v91, v91
	v_fmac_f32_e32 v81, v90, v90
	v_add_f32_e32 v100, v101, v100
	v_add_f32_e32 v80, v81, v80
	v_add_f32_e32 v80, v100, v80
	ds_bpermute_b32 v81, v126, v80
	v_mov_b64_e32 v[98:99], s[4:5]
	v_mad_i64_i32 v[98:99], s[12:13], v210, s66, v[98:99]
	v_lshl_add_u64 v[98:99], v[188:189], 1, v[98:99]
	s_waitcnt lgkmcnt(0)
	v_add_f32_e32 v80, v80, v81
	ds_bpermute_b32 v81, v127, v80
	global_store_dwordx4 v[98:99], v[92:95], off
	global_store_dwordx4 v[96:97], v[84:87], off offset:512
	global_store_dwordx4 v[96:97], v[88:91], off offset:528
	v_cvt_pk_bf16_f32 v82, v84, v85
	v_cvt_pk_bf16_f32 v83, v86, v87
	s_nop 0
	v_cvt_pk_bf16_f32 v84, v88, v89
	v_cvt_pk_bf16_f32 v85, v90, v91
	global_store_dwordx4 v[98:99], v[82:85], off offset:256
	s_and_saveexec_b64 s[46:47], s[38:39]
	s_cbranch_execz .LBB0_734
	v_lshlrev_b64 v[82:83], 7, v[210:211]
	v_lshl_add_u64 v[82:83], s[94:95], 0, v[82:83]
	v_lshl_add_u64 v[82:83], s[42:43], 2, v[82:83]
	s_lshl_b32 s30, s57, 2
	v_lshl_add_u64 v[82:83], v[82:83], 0, s[30:31]
	s_waitcnt lgkmcnt(0)
	v_add_f32_e32 v80, v80, v81
	global_store_dword v[82:83], v80, off
.LBB0_734:
	s_or_b64 exec, exec, s[46:47]
	s_waitcnt vmcnt(18)
	v_pk_add_f32 v[78:79], v[78:79], v[142:143]
	v_pk_add_f32 v[76:77], v[76:77], v[140:141]
	v_mul_f32_e32 v85, v79, v79
	v_mul_f32_e32 v84, v77, v77
	s_waitcnt lgkmcnt(0)
	v_lshl_add_u64 v[80:81], s[82:83], 0, v[212:213]
	v_pk_add_f32 v[72:73], v[72:73], v[132:133]
	v_fmac_f32_e32 v84, v76, v76
	v_fmac_f32_e32 v85, v78, v78
	v_lshl_add_u64 v[80:81], v[188:189], 2, v[80:81]
	v_add_f32_e32 v84, v84, v85
	v_mul_f32_e32 v85, v73, v73
	v_pk_add_f32 v[70:71], v[70:71], v[118:119]
	v_pk_add_f32 v[68:69], v[68:69], v[116:117]
	v_pk_add_f32 v[74:75], v[74:75], v[134:135]
	global_store_dwordx4 v[80:81], v[76:79], off
	global_store_dwordx4 v[80:81], v[72:75], off offset:16
	v_fmac_f32_e32 v85, v72, v72
	v_cvt_pk_bf16_f32 v76, v76, v77
	v_cvt_pk_bf16_f32 v77, v78, v79
	v_cvt_pk_bf16_f32 v78, v72, v73
	v_add_f32_e32 v84, v84, v85
	v_pk_add_f32 v[72:73], v[64:65], v[112:113]
	v_mul_f32_e32 v64, v69, v69
	v_mul_f32_e32 v65, v71, v71
	v_fmac_f32_e32 v64, v68, v68
	v_fmac_f32_e32 v65, v70, v70
	v_mul_f32_e32 v85, v75, v75
	v_add_f32_e32 v64, v64, v65
	v_mul_f32_e32 v65, v73, v73
	v_fmac_f32_e32 v85, v74, v74
	v_cvt_pk_bf16_f32 v79, v74, v75
	v_pk_add_f32 v[74:75], v[66:67], v[114:115]
	v_fmac_f32_e32 v65, v72, v72
	v_add_f32_e32 v64, v64, v65
	v_mul_f32_e32 v65, v75, v75
	v_fmac_f32_e32 v65, v74, v74
	v_add_f32_e32 v84, v85, v84
	v_add_f32_e32 v64, v65, v64
	v_add_f32_e32 v64, v84, v64
	ds_bpermute_b32 v65, v126, v64
	v_mov_b64_e32 v[82:83], s[4:5]
	v_mad_i64_i32 v[82:83], s[12:13], v208, s66, v[82:83]
	v_lshl_add_u64 v[82:83], v[188:189], 1, v[82:83]
	s_waitcnt lgkmcnt(0)
	v_add_f32_e32 v64, v64, v65
	ds_bpermute_b32 v65, v127, v64
	global_store_dwordx4 v[82:83], v[76:79], off
	global_store_dwordx4 v[80:81], v[68:71], off offset:512
	global_store_dwordx4 v[80:81], v[72:75], off offset:528
	v_cvt_pk_bf16_f32 v66, v68, v69
	v_cvt_pk_bf16_f32 v67, v70, v71
	s_nop 0
	v_cvt_pk_bf16_f32 v68, v72, v73
	v_cvt_pk_bf16_f32 v69, v74, v75
	global_store_dwordx4 v[82:83], v[66:69], off offset:256
	s_and_saveexec_b64 s[46:47], s[38:39]
	s_cbranch_execz .LBB0_736
	v_lshlrev_b64 v[66:67], 7, v[208:209]
	v_lshl_add_u64 v[66:67], s[94:95], 0, v[66:67]
	v_lshl_add_u64 v[66:67], s[42:43], 2, v[66:67]
	s_lshl_b32 s30, s57, 2
	v_lshl_add_u64 v[66:67], v[66:67], 0, s[30:31]
	s_waitcnt lgkmcnt(0)
	v_add_f32_e32 v64, v64, v65
	global_store_dword v[66:67], v64, off

; #define PG8_STAGE(bufoff, gbase, voff) do { _Pragma("unroll") for (int _i = 0; _i < 2; ++_i) \
;         __builtin_amdgcn_global_load_lds((const unsigned*)((const char*)(gbase) + (voff)[_i]), (LAS unsigned*)(lds + (bufoff) + ldsw + _i * 8192), 16, 0, 0); } while (0)
; #define PG8_LDA(dst, b, h) do { _Pragma("unroll") for (int m = 0; m < 4; ++m) _Pragma("unroll") for (int k = 0; k < 2; ++k) dst[m][k] = *(const LAS bf16x8*)(lds + PG8_SA(b, h) + aoff + m * 2048 + k * 1024); } while (0)
; #define PG8_LDB(dst, b, h) do { _Pragma("unroll") for (int n = 0; n < 2; ++n) _Pragma("unroll") for (int k = 0; k < 2; ++k) dst[n][k] = *(const LAS bf16x8*)(lds + PG8_SB(b, h) + boff + n * 2048 + k * 1024); } while (0)
; #define PG8_MMA(ai, bj, At, Bt) do { __builtin_amdgcn_s_setprio(1); _Pragma("unroll") for (int m = 0; m < 4; ++m) _Pragma("unroll") for (int n = 0; n < 2; ++n) _Pragma("unroll") for (int k = 0; k < 2; ++k) \
;         acc[ai][bj][m][n] = __builtin_amdgcn_mfma_f32_16x16x32_bf16(Bt[n][k], At[m][k], acc[ai][bj][m][n], 0, 0, 0); __builtin_amdgcn_s_setprio(0); } while (0)
; #define PG8_WAIT_V(n) asm volatile("s_waitcnt vmcnt(" #n ")" ::: "memory")
; #define PG8_WAIT_L(n) asm volatile("s_waitcnt lgkmcnt(" #n ")" ::: "memory")
; #define PG8_BAR __builtin_amdgcn_s_barrier()
; #define PG8_SCHED __builtin_amdgcn_sched_barrier(0)
; template <class Epi, bool ALIGN_EPI>
; __device__ __forceinline__ void gemm_phase(LAS unsigned char* lds, const Gemm g, int G, int cid, const Epi& E) {
;     ...
;             PG8_LDB(B0, 0, 0); PG8_LDB(B1, 0, 1); PG8_SCHED; PG8_LDA(At, 0, 0); PG8_STAGE(PG8_SA(1, 1), a1 + hA, voffA);
;             PG8_WAIT_V(8); PG8_WAIT_L(0); PG8_BAR; PG8_MMA(0, 0, At, B0); PG8_MMA(0, 1, At, B1); PG8_BAR; PG8_SCHED;
;             PG8_LDA(At, 0, 1); PG8_STAGE(PG8_SB(0, 0), b2, voffB); PG8_STAGE(PG8_SB(0, 1), b2 + hB, voffB); PG8_STAGE(PG8_SA(0, 0), a2, voffA);
;             PG8_WAIT_V(8); PG8_WAIT_L(0); PG8_BAR; PG8_MMA(1, 0, At, B0); PG8_MMA(1, 1, At, B1); PG8_BAR; PG8_SCHED;
.LBB0_927:
	s_add_u32 s40, s48, 0x100
	s_addc_u32 s41, s49, 0
	s_add_i32 s6, 0, 0x10000
	s_cmpk_eq_i32 s79, 0x54
	s_cselect_b32 s53, s45, s41
	s_cselect_b32 s52, s44, s40
	s_cselect_b32 s51, s30, s78
	s_cselect_b32 s50, s76, s77
	s_add_i32 s86, 0, 0x14000
	v_add_u32_e32 v144, s6, v243
	v_add_u32_e32 v160, s86, v243
	ds_read_b128 v[128:131], v144
	ds_read_b128 v[132:135], v144 offset:1024
	ds_read_b128 v[140:143], v144 offset:2048
	ds_read_b128 v[144:147], v144 offset:3072
	ds_read_b128 v[148:151], v160
	ds_read_b128 v[152:155], v160 offset:1024
	ds_read_b128 v[156:159], v160 offset:2048
	ds_read_b128 v[160:163], v160 offset:3072
	v_lshl_add_u64 v[198:199], s[48:49], 0, v[210:211]
	s_add_i32 m0, s12, 0xc000
	ds_read_b128 v[164:167], v245
	ds_read_b128 v[168:171], v245 offset:1024
	ds_read_b128 v[172:175], v245 offset:2048
	ds_read_b128 v[176:179], v245 offset:3072
	ds_read_b128 v[180:183], v245 offset:4096
	ds_read_b128 v[184:187], v245 offset:5120
	ds_read_b128 v[188:191], v245 offset:6144
	ds_read_b128 v[214:217], v245 offset:7168
	global_load_lds_dwordx4 v[198:199], off
	v_lshl_add_u64 v[198:199], s[48:49], 0, v[212:213]
	s_add_i32 m0, s12, 0xe000
	s_nop 0
	global_load_lds_dwordx4 v[198:199], off
	s_add_i32 vcc_lo, s79, 2
	s_lshl_b32 vcc_lo, vcc_lo, 15
	s_and_b32 vcc_lo, vcc_lo, 0x1f0000
	s_lshl_b32 vcc_hi, s75, 21
	s_add_i32 vcc_lo, vcc_lo, vcc_hi
	s_lshl_b32 vcc_hi, s25, 3
	s_add_i32 vcc_lo, vcc_lo, vcc_hi
	s_lshl_b32 vcc_hi, s74, 10
	s_add_i32 vcc_lo, vcc_lo, vcc_hi
	s_add_u32 vcc_lo, s82, vcc_lo
	s_addc_u32 vcc_hi, s83, 0
	s_mov_b32 m0, 0x22c00
	s_nop 0
	global_load_lds_dwordx4 v226, vcc
	s_waitcnt vmcnt(9)
	s_waitcnt lgkmcnt(0)
	s_barrier
	s_setprio 1
	s_waitcnt lgkmcnt(0)
	v_mfma_f32_16x16x32_bf16 v[124:127], v[128:131], v[164:167], v[124:127]
	v_mfma_f32_16x16x32_bf16 v[120:123], v[140:143], v[164:167], v[120:123]
	v_mfma_f32_16x16x32_bf16 v[108:111], v[128:131], v[172:175], v[108:111]
	v_mfma_f32_16x16x32_bf16 v[104:107], v[140:143], v[172:175], v[104:107]
	v_mfma_f32_16x16x32_bf16 v[92:95], v[128:131], v[180:183], v[92:95]
	v_mfma_f32_16x16x32_bf16 v[88:91], v[140:143], v[180:183], v[88:91]
	v_mfma_f32_16x16x32_bf16 v[76:79], v[128:131], v[188:191], v[76:79]
	v_mfma_f32_16x16x32_bf16 v[72:75], v[140:143], v[188:191], v[72:75]
	v_mfma_f32_16x16x32_bf16 v[124:127], v[132:135], v[168:171], v[124:127]
	v_mfma_f32_16x16x32_bf16 v[120:123], v[144:147], v[168:171], v[120:123]
	v_mfma_f32_16x16x32_bf16 v[108:111], v[132:135], v[176:179], v[108:111]
	v_mfma_f32_16x16x32_bf16 v[104:107], v[144:147], v[176:179], v[104:107]
	v_mfma_f32_16x16x32_bf16 v[92:95], v[132:135], v[184:187], v[92:95]
	v_mfma_f32_16x16x32_bf16 v[88:91], v[144:147], v[184:187], v[88:91]
	v_mfma_f32_16x16x32_bf16 v[76:79], v[132:135], v[214:217], v[76:79]
	v_mfma_f32_16x16x32_bf16 v[72:75], v[144:147], v[214:217], v[72:75]
	s_setprio 0
	s_setprio 1
	v_mfma_f32_16x16x32_bf16 v[116:119], v[148:151], v[164:167], v[116:119]
	v_mfma_f32_16x16x32_bf16 v[112:115], v[156:159], v[164:167], v[112:115]
	v_mfma_f32_16x16x32_bf16 v[100:103], v[148:151], v[172:175], v[100:103]
	v_mfma_f32_16x16x32_bf16 v[96:99], v[156:159], v[172:175], v[96:99]
	v_mfma_f32_16x16x32_bf16 v[84:87], v[148:151], v[180:183], v[84:87]
	v_mfma_f32_16x16x32_bf16 v[80:83], v[156:159], v[180:183], v[80:83]
	v_mfma_f32_16x16x32_bf16 v[68:71], v[148:151], v[188:191], v[68:71]
	v_mfma_f32_16x16x32_bf16 v[64:67], v[156:159], v[188:191], v[64:67]
	v_mfma_f32_16x16x32_bf16 v[116:119], v[152:155], v[168:171], v[116:119]
	v_mfma_f32_16x16x32_bf16 v[112:115], v[160:163], v[168:171], v[112:115]
	v_mfma_f32_16x16x32_bf16 v[100:103], v[152:155], v[176:179], v[100:103]
	v_mfma_f32_16x16x32_bf16 v[96:99], v[160:163], v[176:179], v[96:99]
	v_mfma_f32_16x16x32_bf16 v[84:87], v[152:155], v[184:187], v[84:87]
	v_mfma_f32_16x16x32_bf16 v[80:83], v[160:163], v[184:187], v[80:83]
	v_mfma_f32_16x16x32_bf16 v[68:71], v[152:155], v[214:217], v[68:71]
	v_mfma_f32_16x16x32_bf16 v[64:67], v[160:163], v[214:217], v[64:67]
	s_setprio 0
	s_barrier
	s_add_i32 s6, s6, s25
	v_lshl_add_u64 v[198:199], s[50:51], 0, v[138:139]
	s_mov_b32 m0, s6
	ds_read_b128 v[164:167], v245 offset:16384
	ds_read_b128 v[168:171], v245 offset:17408
	ds_read_b128 v[172:175], v245 offset:18432
	ds_read_b128 v[176:179], v245 offset:19456
	ds_read_b128 v[180:183], v245 offset:20480
	ds_read_b128 v[184:187], v245 offset:21504
	ds_read_b128 v[188:191], v245 offset:22528
	ds_read_b128 v[214:217], v245 offset:23552
	global_load_lds_dwordx4 v[198:199], off
	s_add_i32 m0, s6, 0x2000
	s_add_u32 s6, s50, 0x2000
	v_lshl_add_u64 v[198:199], s[50:51], 0, v[136:137]
	s_addc_u32 s7, s51, 0
	s_add_i32 s48, s86, s25
	global_load_lds_dwordx4 v[198:199], off
	v_lshl_add_u64 v[198:199], s[6:7], 0, v[138:139]
	s_mov_b32 m0, s48
	v_lshl_add_u64 v[200:201], s[52:53], 0, v[206:207]
	global_load_lds_dwordx4 v[198:199], off
	v_lshl_add_u64 v[198:199], s[6:7], 0, v[136:137]
	s_add_i32 m0, s48, 0x2000
	s_nop 0
	global_load_lds_dwordx4 v[198:199], off
	v_lshl_add_u64 v[198:199], s[52:53], 0, v[208:209]
	s_mov_b32 m0, s12
	s_nop 0
	global_load_lds_dwordx4 v[198:199], off
	s_mov_b32 m0, s13
	s_nop 0
	global_load_lds_dwordx4 v[200:201], off
	s_waitcnt vmcnt(9)
	s_waitcnt lgkmcnt(0)
	s_barrier
; #define PG8_STAGE(bufoff, gbase, voff) do { _Pragma("unroll") for (int _i = 0; _i < 2; ++_i) \
;         __builtin_amdgcn_global_load_lds((const unsigned*)((const char*)(gbase) + (voff)[_i]), (LAS unsigned*)(lds + (bufoff) + ldsw + _i * 8192), 16, 0, 0); } while (0)
; #define PG8_LDA(dst, b, h) do { _Pragma("unroll") for (int m = 0; m < 4; ++m) _Pragma("unroll") for (int k = 0; k < 2; ++k) dst[m][k] = *(const LAS bf16x8*)(lds + PG8_SA(b, h) + aoff + m * 2048 + k * 1024); } while (0)
; #define PG8_LDB(dst, b, h) do { _Pragma("unroll") for (int n = 0; n < 2; ++n) _Pragma("unroll") for (int k = 0; k < 2; ++k) dst[n][k] = *(const LAS bf16x8*)(lds + PG8_SB(b, h) + boff + n * 2048 + k * 1024); } while (0)
; #define PG8_MMA(ai, bj, At, Bt) do { __builtin_amdgcn_s_setprio(1); _Pragma("unroll") for (int m = 0; m < 4; ++m) _Pragma("unroll") for (int n = 0; n < 2; ++n) _Pragma("unroll") for (int k = 0; k < 2; ++k) \
;         acc[ai][bj][m][n] = __builtin_amdgcn_mfma_f32_16x16x32_bf16(Bt[n][k], At[m][k], acc[ai][bj][m][n], 0, 0, 0); __builtin_amdgcn_s_setprio(0); } while (0)
; #define PG8_WAIT_V(n) asm volatile("s_waitcnt vmcnt(" #n ")" ::: "memory")
; #define PG8_WAIT_L(n) asm volatile("s_waitcnt lgkmcnt(" #n ")" ::: "memory")
; #define PG8_BAR __builtin_amdgcn_s_barrier()
; #define PG8_SCHED __builtin_amdgcn_sched_barrier(0)
; template <class Epi, bool ALIGN_EPI>
; __device__ __forceinline__ void gemm_phase(LAS unsigned char* lds, const Gemm g, int G, int cid, const Epi& E) {
;     ...
;             PG8_WAIT_V(8); PG8_WAIT_L(0); PG8_BAR; PG8_MMA(0, 0, At, B0); PG8_MMA(0, 1, At, B1); PG8_BAR; PG8_SCHED;
;             PG8_LDA(At, 0, 1); PG8_STAGE(PG8_SB(0, 0), b2, voffB); PG8_STAGE(PG8_SB(0, 1), b2 + hB, voffB); PG8_STAGE(PG8_SA(0, 0), a2, voffA);
;             PG8_WAIT_V(8); PG8_WAIT_L(0); PG8_BAR; PG8_MMA(1, 0, At, B0); PG8_MMA(1, 1, At, B1); PG8_BAR; PG8_SCHED;
;             PG8_LDB(B0, 1, 0); PG8_LDB(B1, 1, 1); PG8_SCHED; PG8_LDA(At, 1, 0); PG8_STAGE(PG8_SA(0, 1), a2 + hA, voffA);
;             PG8_WAIT_V(8); PG8_WAIT_L(0); PG8_BAR; PG8_MMA(0, 0, At, B0); PG8_MMA(0, 1, At, B1); PG8_BAR; PG8_SCHED;
	s_setprio 1
	s_waitcnt lgkmcnt(0)
	v_mfma_f32_16x16x32_bf16 v[60:63], v[128:131], v[164:167], v[60:63]
	v_mfma_f32_16x16x32_bf16 v[56:59], v[140:143], v[164:167], v[56:59]
	v_mfma_f32_16x16x32_bf16 v[44:47], v[128:131], v[172:175], v[44:47]
	v_mfma_f32_16x16x32_bf16 v[40:43], v[140:143], v[172:175], v[40:43]
	v_mfma_f32_16x16x32_bf16 v[28:31], v[128:131], v[180:183], v[28:31]
	v_mfma_f32_16x16x32_bf16 v[24:27], v[140:143], v[180:183], v[24:27]
	v_mfma_f32_16x16x32_bf16 v[12:15], v[128:131], v[188:191], v[12:15]
	v_mfma_f32_16x16x32_bf16 v[8:11], v[140:143], v[188:191], v[8:11]
	v_mfma_f32_16x16x32_bf16 v[60:63], v[132:135], v[168:171], v[60:63]
	v_mfma_f32_16x16x32_bf16 v[56:59], v[144:147], v[168:171], v[56:59]
	v_mfma_f32_16x16x32_bf16 v[44:47], v[132:135], v[176:179], v[44:47]
	v_mfma_f32_16x16x32_bf16 v[40:43], v[144:147], v[176:179], v[40:43]
	v_mfma_f32_16x16x32_bf16 v[28:31], v[132:135], v[184:187], v[28:31]
	v_mfma_f32_16x16x32_bf16 v[24:27], v[144:147], v[184:187], v[24:27]
	v_mfma_f32_16x16x32_bf16 v[12:15], v[132:135], v[214:217], v[12:15]
	v_mfma_f32_16x16x32_bf16 v[8:11], v[144:147], v[214:217], v[8:11]
	s_setprio 0
	s_setprio 1
	v_mfma_f32_16x16x32_bf16 v[52:55], v[148:151], v[164:167], v[52:55]
	v_mfma_f32_16x16x32_bf16 v[48:51], v[156:159], v[164:167], v[48:51]
	v_mfma_f32_16x16x32_bf16 v[36:39], v[148:151], v[172:175], v[36:39]
	v_mfma_f32_16x16x32_bf16 v[32:35], v[156:159], v[172:175], v[32:35]
	v_mfma_f32_16x16x32_bf16 v[20:23], v[148:151], v[180:183], v[20:23]
	v_mfma_f32_16x16x32_bf16 v[16:19], v[156:159], v[180:183], v[16:19]
	v_mfma_f32_16x16x32_bf16 v[4:7], v[148:151], v[188:191], v[4:7]
	v_mfma_f32_16x16x32_bf16 v[0:3], v[156:159], v[188:191], v[0:3]
	v_mfma_f32_16x16x32_bf16 v[52:55], v[152:155], v[168:171], v[52:55]
	v_mfma_f32_16x16x32_bf16 v[48:51], v[160:163], v[168:171], v[48:51]
	v_mfma_f32_16x16x32_bf16 v[36:39], v[152:155], v[176:179], v[36:39]
	v_mfma_f32_16x16x32_bf16 v[32:35], v[160:163], v[176:179], v[32:35]
	v_mfma_f32_16x16x32_bf16 v[20:23], v[152:155], v[184:187], v[20:23]
	v_mfma_f32_16x16x32_bf16 v[16:19], v[160:163], v[184:187], v[16:19]
	v_mfma_f32_16x16x32_bf16 v[4:7], v[152:155], v[214:217], v[4:7]
	v_mfma_f32_16x16x32_bf16 v[0:3], v[160:163], v[214:217], v[0:3]
	s_setprio 0
	s_barrier
	s_add_i32 s48, 0, 0x18000
	s_add_i32 s49, 0, 0x1c000
	v_add_u32_e32 v144, s48, v243
	v_add_u32_e32 v160, s49, v243
	ds_read_b128 v[128:131], v144
	ds_read_b128 v[132:135], v144 offset:1024
	ds_read_b128 v[140:143], v144 offset:2048
	ds_read_b128 v[144:147], v144 offset:3072
	ds_read_b128 v[148:151], v160
	ds_read_b128 v[152:155], v160 offset:1024
	ds_read_b128 v[156:159], v160 offset:2048
	ds_read_b128 v[160:163], v160 offset:3072
	s_add_u32 s6, s52, 0x160000
	s_addc_u32 s7, s53, 0
	s_mov_b32 m0, s54
	v_lshl_add_u64 v[218:219], s[6:7], 0, v[208:209]
	ds_read_b128 v[164:167], v245 offset:32768
	ds_read_b128 v[168:171], v245 offset:33792
	ds_read_b128 v[172:175], v245 offset:34816
	ds_read_b128 v[176:179], v245 offset:35840
	ds_read_b128 v[180:183], v245 offset:36864
	ds_read_b128 v[184:187], v245 offset:37888
	ds_read_b128 v[188:191], v245 offset:38912
	ds_read_b128 v[214:217], v245 offset:39936
	global_load_lds_dwordx4 v[218:219], off
	v_lshl_add_u64 v[218:219], s[6:7], 0, v[206:207]
	s_mov_b32 m0, s55
	s_nop 0
	global_load_lds_dwordx4 v[218:219], off
	s_waitcnt vmcnt(8)
	s_waitcnt lgkmcnt(0)
	s_barrier
	s_setprio 1
	s_waitcnt lgkmcnt(0)
	v_mfma_f32_16x16x32_bf16 v[124:127], v[128:131], v[164:167], v[124:127]
	v_mfma_f32_16x16x32_bf16 v[120:123], v[140:143], v[164:167], v[120:123]
	v_mfma_f32_16x16x32_bf16 v[108:111], v[128:131], v[172:175], v[108:111]
	v_mfma_f32_16x16x32_bf16 v[104:107], v[140:143], v[172:175], v[104:107]
	v_mfma_f32_16x16x32_bf16 v[92:95], v[128:131], v[180:183], v[92:95]
	v_mfma_f32_16x16x32_bf16 v[88:91], v[140:143], v[180:183], v[88:91]
	v_mfma_f32_16x16x32_bf16 v[76:79], v[128:131], v[188:191], v[76:79]
	v_mfma_f32_16x16x32_bf16 v[72:75], v[140:143], v[188:191], v[72:75]
	v_mfma_f32_16x16x32_bf16 v[124:127], v[132:135], v[168:171], v[124:127]
	v_mfma_f32_16x16x32_bf16 v[120:123], v[144:147], v[168:171], v[120:123]
	v_mfma_f32_16x16x32_bf16 v[108:111], v[132:135], v[176:179], v[108:111]
	v_mfma_f32_16x16x32_bf16 v[104:107], v[144:147], v[176:179], v[104:107]
	v_mfma_f32_16x16x32_bf16 v[92:95], v[132:135], v[184:187], v[92:95]
	v_mfma_f32_16x16x32_bf16 v[88:91], v[144:147], v[184:187], v[88:91]
	v_mfma_f32_16x16x32_bf16 v[76:79], v[132:135], v[214:217], v[76:79]
	v_mfma_f32_16x16x32_bf16 v[72:75], v[144:147], v[214:217], v[72:75]
	s_setprio 0
	s_setprio 1
	v_mfma_f32_16x16x32_bf16 v[116:119], v[148:151], v[164:167], v[116:119]
	v_mfma_f32_16x16x32_bf16 v[112:115], v[156:159], v[164:167], v[112:115]
	v_mfma_f32_16x16x32_bf16 v[100:103], v[148:151], v[172:175], v[100:103]
	v_mfma_f32_16x16x32_bf16 v[96:99], v[156:159], v[172:175], v[96:99]
	v_mfma_f32_16x16x32_bf16 v[84:87], v[148:151], v[180:183], v[84:87]
	v_mfma_f32_16x16x32_bf16 v[80:83], v[156:159], v[180:183], v[80:83]
	v_mfma_f32_16x16x32_bf16 v[68:71], v[148:151], v[188:191], v[68:71]
	v_mfma_f32_16x16x32_bf16 v[64:67], v[156:159], v[188:191], v[64:67]
	v_mfma_f32_16x16x32_bf16 v[116:119], v[152:155], v[168:171], v[116:119]
	v_mfma_f32_16x16x32_bf16 v[112:115], v[160:163], v[168:171], v[112:115]
	v_mfma_f32_16x16x32_bf16 v[100:103], v[152:155], v[176:179], v[100:103]
	v_mfma_f32_16x16x32_bf16 v[96:99], v[160:163], v[176:179], v[96:99]
	v_mfma_f32_16x16x32_bf16 v[84:87], v[152:155], v[184:187], v[84:87]
	v_mfma_f32_16x16x32_bf16 v[80:83], v[160:163], v[184:187], v[80:83]
	v_mfma_f32_16x16x32_bf16 v[68:71], v[152:155], v[214:217], v[68:71]
	v_mfma_f32_16x16x32_bf16 v[64:67], v[160:163], v[214:217], v[64:67]
	s_setprio 0
	s_barrier
; #define PG8_MMA(ai, bj, At, Bt) do { __builtin_amdgcn_s_setprio(1); _Pragma("unroll") for (int m = 0; m < 4; ++m) _Pragma("unroll") for (int n = 0; n < 2; ++n) _Pragma("unroll") for (int k = 0; k < 2; ++k) \
;         acc[ai][bj][m][n] = __builtin_amdgcn_mfma_f32_16x16x32_bf16(Bt[n][k], At[m][k], acc[ai][bj][m][n], 0, 0, 0); __builtin_amdgcn_s_setprio(0); } while (0)
; #define PG8_WAIT_V(n) asm volatile("s_waitcnt vmcnt(" #n ")" ::: "memory")
; #define PG8_WAIT_L(n) asm volatile("s_waitcnt lgkmcnt(" #n ")" ::: "memory")
; #define PG8_BAR __builtin_amdgcn_s_barrier()
; #define PG8_SCHED __builtin_amdgcn_sched_barrier(0)
; template <class Epi, bool ALIGN_EPI>
; __device__ __forceinline__ void gemm_phase(LAS unsigned char* lds, const Gemm g, int G, int cid, const Epi& E) {
;     ...
;             PG8_WAIT_V(8); PG8_WAIT_L(0); PG8_BAR; PG8_MMA(1, 0, At, B0); PG8_MMA(1, 1, At, B1); PG8_BAR; PG8_SCHED;
;         }
;     __device__ __forceinline__ void operator()(const f32x4 (&acc)[2][2][4][2], const Unit& u, int wr, int wc, int fr, int fq, const LAS float*) const {
;     ...
;         for (int am = 0; am < NB; ++am) { const int ai = am / (NB / 2), m0 = (am % (NB / 2)) * MB;
;             f32x4 xo[4][2][2];
; #pragma unroll
;             for (int m = m0; m < m0 + MB; ++m) { const float* xr = Xs + (size_t)(row0 + ai * HALF + m * 16) * DM + col0;
; #pragma unroll
;                 for (int bj = 0; bj < 2; ++bj) { xo[m][bj][0] = *(const f32x4*)(xr + bj * HALF); xo[m][bj][1] = *(const f32x4*)(xr + bj * HALF + 4); } }
; #pragma unroll
;             for (int m = m0; m < m0 + MB; ++m) { const int row = row0 + ai * HALF + m * 16; float ss = 0.f;
;                 float* xr = X + (size_t)row * DM + col0; bf16_t* xb = XB + (size_t)row * ALD + col0;
; #pragma unroll
;                 for (int bj = 0; bj < 2; ++bj) { f32x4 x0 = xo[m][bj][0], x1 = xo[m][bj][1];
;                     if (HB) { x0 += (acc[ai][bj][m][0] + bv[bj][0]) * sv[bj][0]; x1 += (acc[ai][bj][m][1] + bv[bj][1]) * sv[bj][1]; } else { x0 += acc[ai][bj][m][0]; x1 += acc[ai][bj][m][1]; }
	s_add_u32 s6, s50, 0x40000
	s_addc_u32 s7, s51, 0
	s_add_i32 s48, s48, s25
	v_lshl_add_u64 v[218:219], s[6:7], 0, v[138:139]
	s_mov_b32 m0, s48
	ds_read_b128 v[164:167], v245 offset:49152
	ds_read_b128 v[168:171], v245 offset:50176
	ds_read_b128 v[172:175], v245 offset:51200
	ds_read_b128 v[176:179], v245 offset:52224
	ds_read_b128 v[180:183], v245 offset:53248
	ds_read_b128 v[184:187], v245 offset:54272
	ds_read_b128 v[188:191], v245 offset:55296
	ds_read_b128 v[214:217], v245 offset:56320
	global_load_lds_dwordx4 v[218:219], off
	s_add_i32 m0, s48, 0x2000
	v_lshl_add_u64 v[218:219], s[6:7], 0, v[136:137]
	s_add_u32 s6, s50, 0x42000
	s_addc_u32 s7, s51, 0
	s_add_i32 s48, s49, s25
	global_load_lds_dwordx4 v[218:219], off
	v_lshl_add_u64 v[218:219], s[6:7], 0, v[138:139]
	s_mov_b32 m0, s48
	v_lshl_add_u64 v[198:199], v[198:199], 0, s[36:37]
	global_load_lds_dwordx4 v[218:219], off
	v_lshl_add_u64 v[218:219], s[6:7], 0, v[136:137]
	s_add_i32 m0, s48, 0x2000
	s_nop 0
	global_load_lds_dwordx4 v[218:219], off
	s_mov_b32 m0, s57
	s_nop 0
	global_load_lds_dwordx4 v[198:199], off
	v_lshl_add_u64 v[198:199], v[200:201], 0, s[36:37]
	s_mov_b32 m0, s58
	s_nop 0
	global_load_lds_dwordx4 v[198:199], off
	s_waitcnt vmcnt(8)
	s_waitcnt lgkmcnt(0)
	s_barrier
	s_setprio 1
	s_waitcnt lgkmcnt(0)
	v_mfma_f32_16x16x32_bf16 v[60:63], v[128:131], v[164:167], v[60:63]
	v_mfma_f32_16x16x32_bf16 v[56:59], v[140:143], v[164:167], v[56:59]
	v_mfma_f32_16x16x32_bf16 v[44:47], v[128:131], v[172:175], v[44:47]
	v_mfma_f32_16x16x32_bf16 v[40:43], v[140:143], v[172:175], v[40:43]
	v_mfma_f32_16x16x32_bf16 v[28:31], v[128:131], v[180:183], v[28:31]
	v_mfma_f32_16x16x32_bf16 v[24:27], v[140:143], v[180:183], v[24:27]
	v_mfma_f32_16x16x32_bf16 v[12:15], v[128:131], v[188:191], v[12:15]
	v_mfma_f32_16x16x32_bf16 v[8:11], v[140:143], v[188:191], v[8:11]
	v_mfma_f32_16x16x32_bf16 v[60:63], v[132:135], v[168:171], v[60:63]
	v_mfma_f32_16x16x32_bf16 v[56:59], v[144:147], v[168:171], v[56:59]
	v_mfma_f32_16x16x32_bf16 v[44:47], v[132:135], v[176:179], v[44:47]
	v_mfma_f32_16x16x32_bf16 v[40:43], v[144:147], v[176:179], v[40:43]
	v_mfma_f32_16x16x32_bf16 v[28:31], v[132:135], v[184:187], v[28:31]
	v_mfma_f32_16x16x32_bf16 v[24:27], v[144:147], v[184:187], v[24:27]
	v_mfma_f32_16x16x32_bf16 v[12:15], v[132:135], v[214:217], v[12:15]
	v_mfma_f32_16x16x32_bf16 v[8:11], v[144:147], v[214:217], v[8:11]
	s_setprio 0
	s_setprio 1
	v_mfma_f32_16x16x32_bf16 v[52:55], v[148:151], v[164:167], v[52:55]
	v_mfma_f32_16x16x32_bf16 v[48:51], v[156:159], v[164:167], v[48:51]
	v_mfma_f32_16x16x32_bf16 v[36:39], v[148:151], v[172:175], v[36:39]
	v_mfma_f32_16x16x32_bf16 v[32:35], v[156:159], v[172:175], v[32:35]
	v_mfma_f32_16x16x32_bf16 v[20:23], v[148:151], v[180:183], v[20:23]
	v_mfma_f32_16x16x32_bf16 v[16:19], v[156:159], v[180:183], v[16:19]
	v_mfma_f32_16x16x32_bf16 v[4:7], v[148:151], v[188:191], v[4:7]
	v_mfma_f32_16x16x32_bf16 v[0:3], v[156:159], v[188:191], v[0:3]
	v_mfma_f32_16x16x32_bf16 v[52:55], v[152:155], v[168:171], v[52:55]
	v_mfma_f32_16x16x32_bf16 v[48:51], v[160:163], v[168:171], v[48:51]
	v_mfma_f32_16x16x32_bf16 v[36:39], v[152:155], v[176:179], v[36:39]
	v_mfma_f32_16x16x32_bf16 v[32:35], v[160:163], v[176:179], v[32:35]
	v_mfma_f32_16x16x32_bf16 v[20:23], v[152:155], v[184:187], v[20:23]
	v_mfma_f32_16x16x32_bf16 v[16:19], v[160:163], v[184:187], v[16:19]
	v_mfma_f32_16x16x32_bf16 v[4:7], v[152:155], v[214:217], v[4:7]
	v_mfma_f32_16x16x32_bf16 v[0:3], v[160:163], v[214:217], v[0:3]
	s_setprio 0
	s_barrier
	s_add_i32 s79, s79, 2
	s_add_u32 s77, s77, 0x80000
	s_addc_u32 s78, s78, 0
	s_cmpk_gt_u32 s79, 0x55
	s_mov_b64 s[48:49], s[40:41]
	s_cbranch_scc0 .LBB0_927
	v_lshl_or_b32 v214, s74, 8, v244
	v_lshl_add_u32 v216, s75, 8, v197
	v_ashrrev_i32_e32 v215, 31, v214
	v_lshlrev_b64 v[198:199], 2, v[214:215]
	v_ashrrev_i32_e32 v217, 31, v216
	v_or_b32_e32 v226, 16, v216
	v_lshl_add_u64 v[218:219], s[82:83], 0, v[198:199]
	v_lshlrev_b64 v[200:201], 13, v[216:217]
	v_ashrrev_i32_e32 v227, 31, v226
	v_or_b32_e32 v222, 32, v216
	v_or_b32_e32 v220, 48, v216
	v_lshl_add_u64 v[128:129], v[218:219], 0, v[200:201]
	v_lshlrev_b64 v[230:231], 13, v[226:227]
	v_ashrrev_i32_e32 v223, 31, v222
	v_ashrrev_i32_e32 v221, 31, v220
	global_load_dwordx4 v[188:191], v[128:129], off offset:16
	global_load_dwordx4 v[246:249], v[128:129], off
	global_load_dwordx4 v[180:183], v[128:129], off offset:528
	global_load_dwordx4 v[184:187], v[128:129], off offset:512
	v_lshl_add_u64 v[128:129], v[218:219], 0, v[230:231]
	v_lshlrev_b64 v[228:229], 13, v[222:223]
	v_lshlrev_b64 v[224:225], 13, v[220:221]
	global_load_dwordx4 v[172:175], v[128:129], off offset:16
	global_load_dwordx4 v[176:179], v[128:129], off
	global_load_dwordx4 v[164:167], v[128:129], off offset:528
	global_load_dwordx4 v[168:171], v[128:129], off offset:512
	v_lshl_add_u64 v[128:129], v[218:219], 0, v[228:229]
	v_lshl_add_u64 v[132:133], v[218:219], 0, v[224:225]
	global_load_dwordx4 v[156:159], v[128:129], off offset:16
	global_load_dwordx4 v[160:163], v[128:129], off
	global_load_dwordx4 v[148:151], v[128:129], off offset:528
	global_load_dwordx4 v[152:155], v[128:129], off offset:512
	global_load_dwordx4 v[140:143], v[132:133], off offset:16
	global_load_dwordx4 v[144:147], v[132:133], off
	s_nop 0
	global_load_dwordx4 v[128:131], v[132:133], off offset:528
	s_nop 0
	global_load_dwordx4 v[132:135], v[132:133], off offset:512
	v_lshl_add_u64 v[200:201], s[82:83], 0, v[200:201]
	v_lshl_add_u64 v[234:235], v[200:201], 0, v[198:199]
	v_mov_b64_e32 v[198:199], s[4:5]
	v_mad_i64_i32 v[198:199], s[6:7], v216, s66, v[198:199]
	v_lshl_add_u64 v[232:233], v[214:215], 1, v[198:199]
	s_and_b64 vcc, exec, s[28:29]
	s_waitcnt vmcnt(12)
	v_pk_add_f32 v[122:123], v[122:123], v[190:191]
	v_pk_add_f32 v[126:127], v[126:127], v[248:249]
	v_pk_add_f32 v[124:125], v[124:125], v[246:247]
	v_pk_add_f32 v[120:121], v[120:121], v[188:189]
	global_store_dwordx4 v[234:235], v[124:127], off
	global_store_dwordx4 v[234:235], v[120:123], off offset:16
	v_cvt_pk_bf16_f32 v188, v124, v125
	v_cvt_pk_bf16_f32 v189, v126, v127
	v_cvt_pk_bf16_f32 v190, v120, v121
	v_cvt_pk_bf16_f32 v191, v122, v123
	s_cbranch_vccz .LBB0_930
	global_store_dwordx4 v[232:233], v[188:191], off

;     __device__ __forceinline__ void operator()(const f32x4 (&acc)[2][2][4][2], const Unit& u, int wr, int wc, int fr, int fq, const LAS float*) const {
;     ...
;             for (int m = m0; m < m0 + MB; ++m) { const int row = row0 + ai * HALF + m * 16; float ss = 0.f;
;                 float* xr = X + (size_t)row * DM + col0; bf16_t* xb = XB + (size_t)row * ALD + col0;
; #pragma unroll
;                 for (int bj = 0; bj < 2; ++bj) { f32x4 x0 = xo[m][bj][0], x1 = xo[m][bj][1];
;                     if (HB) { x0 += (acc[ai][bj][m][0] + bv[bj][0]) * sv[bj][0]; x1 += (acc[ai][bj][m][1] + bv[bj][1]) * sv[bj][1]; } else { x0 += acc[ai][bj][m][0]; x1 += acc[ai][bj][m][1]; }
;                     *(f32x4*)(xr + bj * HALF) = x0; *(f32x4*)(xr + bj * HALF + 4) = x1;
.LBB0_934:
	s_or_b64 exec, exec, s[50:51]
	s_waitcnt vmcnt(12)
	s_waitcnt lgkmcnt(0)
	v_lshl_add_u64 v[112:113], s[82:83], 0, v[230:231]
	v_lshl_add_u64 v[118:119], v[214:215], 2, v[112:113]
	v_mov_b64_e32 v[112:113], s[4:5]
	v_mad_i64_i32 v[112:113], s[6:7], v226, s66, v[112:113]
	v_lshl_add_u64 v[116:117], v[214:215], 1, v[112:113]
	v_pk_add_f32 v[110:111], v[110:111], v[178:179]
	v_pk_add_f32 v[108:109], v[108:109], v[176:177]
	v_pk_add_f32 v[106:107], v[106:107], v[174:175]
	v_pk_add_f32 v[104:105], v[104:105], v[172:173]
	s_and_b64 vcc, exec, s[40:41]
	global_store_dwordx4 v[118:119], v[108:111], off
	global_store_dwordx4 v[118:119], v[104:107], off offset:16
	v_cvt_pk_bf16_f32 v112, v108, v109
	v_cvt_pk_bf16_f32 v113, v110, v111
	v_cvt_pk_bf16_f32 v114, v104, v105
	v_cvt_pk_bf16_f32 v115, v106, v107
	s_cbranch_vccnz .LBB0_936
	global_store_dwordx4 v[116:117], v[112:115], off

;     __device__ __forceinline__ void operator()(const f32x4 (&acc)[2][2][4][2], const Unit& u, int wr, int wc, int fr, int fq, const LAS float*) const {
;     ...
;             for (int m = m0; m < m0 + MB; ++m) { const int row = row0 + ai * HALF + m * 16; float ss = 0.f;
;                 float* xr = X + (size_t)row * DM + col0; bf16_t* xb = XB + (size_t)row * ALD + col0;
; #pragma unroll
;                 for (int bj = 0; bj < 2; ++bj) { f32x4 x0 = xo[m][bj][0], x1 = xo[m][bj][1];
;                     if (HB) { x0 += (acc[ai][bj][m][0] + bv[bj][0]) * sv[bj][0]; x1 += (acc[ai][bj][m][1] + bv[bj][1]) * sv[bj][1]; } else { x0 += acc[ai][bj][m][0]; x1 += acc[ai][bj][m][1]; }
;                     *(f32x4*)(xr + bj * HALF) = x0; *(f32x4*)(xr + bj * HALF + 4) = x1;
.LBB0_940:
	s_or_b64 exec, exec, s[50:51]
	s_waitcnt vmcnt(12)
	s_waitcnt lgkmcnt(0)
	v_lshl_add_u64 v[96:97], s[82:83], 0, v[228:229]
	v_lshl_add_u64 v[102:103], v[214:215], 2, v[96:97]
	v_mov_b64_e32 v[96:97], s[4:5]
	v_mad_i64_i32 v[96:97], s[6:7], v222, s66, v[96:97]
	v_lshl_add_u64 v[100:101], v[214:215], 1, v[96:97]
	v_pk_add_f32 v[94:95], v[94:95], v[162:163]
	v_pk_add_f32 v[92:93], v[92:93], v[160:161]
	v_pk_add_f32 v[90:91], v[90:91], v[158:159]
	v_pk_add_f32 v[88:89], v[88:89], v[156:157]
	s_and_b64 vcc, exec, s[40:41]
	global_store_dwordx4 v[102:103], v[92:95], off
	global_store_dwordx4 v[102:103], v[88:91], off offset:16
	v_cvt_pk_bf16_f32 v96, v92, v93
	v_cvt_pk_bf16_f32 v97, v94, v95
	v_cvt_pk_bf16_f32 v98, v88, v89
	v_cvt_pk_bf16_f32 v99, v90, v91
	s_cbranch_vccnz .LBB0_942
	global_store_dwordx4 v[100:101], v[96:99], off

;     __device__ __forceinline__ void operator()(const f32x4 (&acc)[2][2][4][2], const Unit& u, int wr, int wc, int fr, int fq, const LAS float*) const {
;     ...
;             for (int m = m0; m < m0 + MB; ++m) { const int row = row0 + ai * HALF + m * 16; float ss = 0.f;
;                 float* xr = X + (size_t)row * DM + col0; bf16_t* xb = XB + (size_t)row * ALD + col0;
; #pragma unroll
;                 for (int bj = 0; bj < 2; ++bj) { f32x4 x0 = xo[m][bj][0], x1 = xo[m][bj][1];
;                     if (HB) { x0 += (acc[ai][bj][m][0] + bv[bj][0]) * sv[bj][0]; x1 += (acc[ai][bj][m][1] + bv[bj][1]) * sv[bj][1]; } else { x0 += acc[ai][bj][m][0]; x1 += acc[ai][bj][m][1]; }
;                     *(f32x4*)(xr + bj * HALF) = x0; *(f32x4*)(xr + bj * HALF + 4) = x1;
.LBB0_946:
	s_or_b64 exec, exec, s[50:51]
	s_waitcnt vmcnt(12)
	s_waitcnt lgkmcnt(0)
	v_lshl_add_u64 v[80:81], s[82:83], 0, v[224:225]
	v_lshl_add_u64 v[86:87], v[214:215], 2, v[80:81]
	v_mov_b64_e32 v[80:81], s[4:5]
	v_mad_i64_i32 v[80:81], s[6:7], v220, s66, v[80:81]
	v_lshl_add_u64 v[84:85], v[214:215], 1, v[80:81]
	v_pk_add_f32 v[78:79], v[78:79], v[146:147]
	v_pk_add_f32 v[76:77], v[76:77], v[144:145]
	v_pk_add_f32 v[74:75], v[74:75], v[142:143]
	v_pk_add_f32 v[72:73], v[72:73], v[140:141]
	s_and_b64 vcc, exec, s[40:41]
	global_store_dwordx4 v[86:87], v[76:79], off
	global_store_dwordx4 v[86:87], v[72:75], off offset:16
	v_cvt_pk_bf16_f32 v80, v76, v77
	v_cvt_pk_bf16_f32 v81, v78, v79
	v_cvt_pk_bf16_f32 v82, v72, v73
	v_cvt_pk_bf16_f32 v83, v74, v75
	s_cbranch_vccnz .LBB0_948
	global_store_dwordx4 v[84:85], v[80:83], off
